# phase E K loop: LDS-DMA loads use scalar base advanced per K step plus precomputed lane offsets (no per-load 64-bit VALU address math or readfirstlane)
# speedup vs baseline: 1.0093x; 1.0093x over previous
; DI void gemm_tile(const bf16_t* __restrict__ A, int lda, const bf16_t* __restrict__ Bt, int ldb, int bvalid, int K, f32x4 (&acc)[4][4], char* lds, bool preloaded = false) {
;     ...
;   const bf16_t* ap = A + (size_t)lr * lda + ((lc ^ ((lr >> 1) & 7)) << 3);
;   const bf16_t* bp = Bt + ((lc ^ ((lr >> 1) & 7)) << 3);
;   typedef __attribute__((address_space(1))) const unsigned gptr_t;
;   typedef __attribute__((address_space(3))) unsigned lptr_t;
;   const unsigned lbase = (unsigned)(size_t)lds + (unsigned)tid * 16u;
; DI void phaseE_tile(const P& p, int layer, int mt, int nt, char* lds) {
;     ...
;   const int col = col0 + wn * 64 + fr * 4;
;   f32x4 xr[16];
; #pragma unroll
;   for (int ps = 0; ps < 16; ++ps) {
;     const int row = row0 + ps * 8 + wm * 4 + fq;
;     const float* xin = (layer == 0) ? ((row < NTP) ? p.x_p + (size_t)row * DM : p.x_s + (size_t)(row - NTP) * DM) : XF + (size_t)row * DM;
;     xr[ps] = __builtin_nontemporal_load((const f32x4*)(xin + col));
;   }
;   gemm_tile((const bf16_t*)(p.ws + W_MERGED) + (size_t)row0 * LDX, LDX, (const bf16_t*)(p.ws + W_WO) + ((size_t)layer * 1024 + col0) * LDX, LDX, 128, 1024, acc, lds);
.LBB0_169:
	s_mul_i32 s8, s10, 0x880
	s_mul_hi_i32 s9, s10, 0x880
	s_add_u32 s24, s58, s8
	s_addc_u32 s25, s59, s9
	s_add_u32 s40, s24, 0x80
	s_addc_u32 s41, s25, 0
	s_ashr_i32 s23, s22, 31
	s_add_u32 s26, s4, s22
	s_addc_u32 s23, s5, s23
	v_mov_b32_e32 v76, v158
	s_mulk_i32 s23, 0x880
	s_mul_hi_u32 s27, s26, 0x880
	s_add_i32 s27, s27, s23
	v_lshrrev_b32_e32 v78, 4, v76
	s_mulk_i32 s26, 0x880
	v_readlane_b32 s28, v240, 31
	v_xor_b32_e32 v0, v78, v76
	v_readlane_b32 s29, v240, 32
	s_add_u32 s26, s28, s26
	v_ashrrev_i32_e32 v77, 3, v76
	v_mov_b64_e32 v[66:67], s[24:25]
	s_movk_i32 s28, 0x880
	v_lshlrev_b32_e32 v0, 4, v0
	s_addc_u32 s27, s29, s27
	s_add_u32 s42, s26, 0x80
	s_addc_u32 s43, s27, 0
	v_mad_i64_i32 v[66:67], s[24:25], v77, s28, v[66:67]
	v_and_b32_e32 v0, 0x70, v0
	v_lshl_add_u64 v[66:67], v[66:67], 0, v[0:1]
	v_lshl_add_u64 v[68:69], s[26:27], 0, v[0:1]
	v_lshlrev_b32_e32 v145, 4, v76
	v_and_b32_e32 v0, 0x7f, v77
	v_add_u32_e32 v72, 0x4000, v145
	v_readfirstlane_b32 s24, v145
	v_mul_u32_u24_e32 v0, 0x440, v0
	s_mov_b32 m0, s24
	v_lshlrev_b32_e32 v0, 1, v0
	v_readfirstlane_b32 s24, v72
	global_load_lds_dwordx4 v[66:67], off
	v_lshl_add_u64 v[70:71], v[68:69], 0, v[0:1]
	s_mov_b32 m0, s24
	s_mov_b64 s[24:25], 0x11000
	v_add_u32_e32 v72, 0x1000, v145
	global_load_lds_dwordx4 v[70:71], off
	v_lshl_add_u64 v[70:71], v[66:67], 0, s[24:25]
	v_readfirstlane_b32 s24, v72
	s_mov_b32 m0, s24
	v_add_u32_e32 v74, 0x5000, v145
	global_load_lds_dwordx4 v[70:71], off
	v_add_u32_e32 v70, 32, v77
	v_and_b32_e32 v70, 0x7f, v70
	v_mul_u32_u24_e32 v70, 0x440, v70
	v_lshlrev_b32_e32 v70, 1, v70
	v_mov_b32_e32 v71, v1
	v_readfirstlane_b32 s24, v74
	v_lshl_add_u64 v[72:73], v[68:69], 0, v[70:71]
	s_mov_b32 m0, s24
	s_mov_b64 s[24:25], 0x22000
	v_add_u32_e32 v74, 0x2000, v145
	global_load_lds_dwordx4 v[72:73], off
	v_lshl_add_u64 v[72:73], v[66:67], 0, s[24:25]
	v_readfirstlane_b32 s24, v74
	s_mov_b32 m0, s24
	v_add_u32_e32 v82, 0x6000, v145
	global_load_lds_dwordx4 v[72:73], off
	v_bitop3_b32 v72, v77, 64, v166 bitop3:0x6c
	v_mul_u32_u24_e32 v72, 0x440, v72
	v_lshlrev_b32_e32 v72, 1, v72
	v_mov_b32_e32 v73, v1
	v_readfirstlane_b32 s24, v82
	v_lshl_add_u64 v[74:75], v[68:69], 0, v[72:73]
	s_mov_b32 m0, s24
	s_mov_b64 s[24:25], 0x33000
	global_load_lds_dwordx4 v[74:75], off
	v_add_u32_e32 v74, 0x3000, v145
	v_lshl_add_u64 v[66:67], v[66:67], 0, s[24:25]
	v_readfirstlane_b32 s24, v74
	s_mov_b32 m0, s24
	v_add_u32_e32 v74, 0x7000, v145
	global_load_lds_dwordx4 v[66:67], off
	v_add_u32_e32 v66, 0x60, v77
	v_and_b32_e32 v66, 0x7f, v66
	v_mul_u32_u24_e32 v66, 0x440, v66
	v_lshlrev_b32_e32 v66, 1, v66
	v_mov_b32_e32 v67, v1
	v_readfirstlane_b32 s24, v74
	v_lshl_add_u64 v[68:69], v[68:69], 0, v[66:67]
	s_mov_b32 m0, s24
	v_readfirstlane_b32 s23, v76
	global_load_lds_dwordx4 v[68:69], off
	global_load_dwordx4 v[2:5], v242, s[36:37] nt
	s_add_u32 s36, s36, 0x8000
	s_addc_u32 s37, s37, 0
	global_load_dwordx4 v[6:9], v242, s[36:37] nt
	s_add_u32 s36, s36, 0x8000
	s_addc_u32 s37, s37, 0
	global_load_dwordx4 v[10:13], v242, s[36:37] nt
	s_add_u32 s36, s36, 0x8000
	s_addc_u32 s37, s37, 0
	global_load_dwordx4 v[14:17], v242, s[36:37] nt
	s_add_u32 s36, s36, 0x8000
	s_addc_u32 s37, s37, 0
	global_load_dwordx4 v[18:21], v242, s[36:37] nt
	s_add_u32 s36, s36, 0x8000
	s_addc_u32 s37, s37, 0
	global_load_dwordx4 v[22:25], v242, s[36:37] nt
	s_add_u32 s36, s36, 0x8000
	s_addc_u32 s37, s37, 0
	global_load_dwordx4 v[26:29], v242, s[36:37] nt
	s_add_u32 s36, s36, 0x8000
	s_addc_u32 s37, s37, 0
	global_load_dwordx4 v[30:33], v242, s[36:37] nt
	s_add_u32 s36, s36, 0x8000
	s_addc_u32 s37, s37, 0
	global_load_dwordx4 v[34:37], v242, s[36:37] nt
	s_add_u32 s36, s36, 0x8000
	s_addc_u32 s37, s37, 0
	global_load_dwordx4 v[38:41], v242, s[36:37] nt
	s_add_u32 s36, s36, 0x8000
	s_addc_u32 s37, s37, 0
	global_load_dwordx4 v[42:45], v242, s[36:37] nt
	s_add_u32 s36, s36, 0x8000
	s_addc_u32 s37, s37, 0
	global_load_dwordx4 v[46:49], v242, s[36:37] nt
	s_add_u32 s36, s36, 0x8000
	s_addc_u32 s37, s37, 0
	global_load_dwordx4 v[50:53], v242, s[36:37] nt
	s_add_u32 s36, s36, 0x8000
	s_addc_u32 s37, s37, 0
	global_load_dwordx4 v[54:57], v242, s[36:37] nt
	s_add_u32 s36, s36, 0x8000
	s_addc_u32 s37, s37, 0
	global_load_dwordx4 v[58:61], v242, s[36:37] nt
	s_add_u32 s36, s36, 0x8000
	s_addc_u32 s37, s37, 0
	global_load_dwordx4 v[62:65], v242, s[36:37] nt
	s_lshl_b32 s24, s23, 7
	v_lshlrev_b32_e32 v68, 7, v76
	s_lshl_b32 s23, s23, 6
	v_bfe_u32 v79, v76, 4, 2
	v_lshrrev_b32_e32 v80, 1, v76
	v_bfe_u32 v81, v76, 1, 3
	s_and_b32 s24, s24, 0x2000
	v_and_b32_e32 v68, 0x780, v68
	s_and_b32 s23, s23, 0xffffe000
	v_or_b32_e32 v146, s24, v68
	v_bitop3_b32 v69, v80, v79, 7 bitop3:0x6c
	v_or_b32_e32 v148, s23, v68
	v_bitop3_b32 v68, v79, v81, 4 bitop3:0x36
	v_lshlrev_b32_e32 v149, 4, v69
	v_lshlrev_b32_e32 v147, 4, v68
	v_mov_b64_e32 v[68:69], s[8:9]
	v_bitop3_b32 v74, v78, 7, v76 bitop3:0x48
	v_mad_i64_i32 v[68:69], s[8:9], v77, s28, v[68:69]
	v_lshlrev_b32_e32 v74, 4, v74
	v_or_b32_e32 v68, v68, v74
	s_mul_hi_i32 s8, s22, 0x880
	s_mulk_i32 s22, 0x880
	v_lshl_add_u64 v[132:133], s[90:91], 0, v[68:69]
	v_or_b32_e32 v68, s22, v74
	v_mov_b32_e32 v69, s8
	v_lshl_add_u64 v[70:71], v[68:69], 0, v[70:71]
	v_lshl_add_u64 v[66:67], v[68:69], 0, v[66:67]
	v_lshl_add_u64 v[74:75], v[68:69], 0, v[0:1]
	v_lshl_add_u64 v[136:137], s[6:7], 0, v[70:71]
	v_lshl_add_u64 v[70:71], v[68:69], 0, v[72:73]
	v_lshl_add_u64 v[140:141], s[6:7], 0, v[66:67]
	v_mov_b32_e32 v66, 0
	v_lshl_add_u64 v[134:135], s[6:7], 0, v[74:75]
	v_lshl_add_u64 v[138:139], s[6:7], 0, v[70:71]
	s_mov_b64 s[8:9], 0
	s_mov_b32 s22, 0
	v_mov_b32_e32 v67, v66
; #define MFMA16(a, b, c) __builtin_amdgcn_mfma_f32_16x16x32_bf16((a), (b), (c), 0, 0, 0)
; DI void gemm_tile(const bf16_t* __restrict__ A, int lda, const bf16_t* __restrict__ Bt, int ldb, int bvalid, int K, f32x4 (&acc)[4][4], char* lds, bool preloaded = false) {
;     ...
;   const bf16_t* ap = A + (size_t)lr * lda + ((lc ^ ((lr >> 1) & 7)) << 3);
;   const bf16_t* bp = Bt + ((lc ^ ((lr >> 1) & 7)) << 3);
;   typedef __attribute__((address_space(1))) const unsigned gptr_t;
;   typedef __attribute__((address_space(3))) unsigned lptr_t;
;   const unsigned lbase = (unsigned)(size_t)lds + (unsigned)tid * 16u;
;     ...
;   auto compute = [&](int st) {
;     const char* base = lds + st * 32768;
;     bf16x8 af[2][4], bfr[2][4];
; #pragma unroll
;     for (int s = 0; s < 2; ++s) {
;       const int ch = ((4 * s + fq) ^ fx) << 4;
; #pragma unroll
;       for (int mi = 0; mi < 4; ++mi) af[s][mi] = *(const bf16x8*)(base + (wm * 64 + mi * 16 + fr) * 128 + ch);
; #pragma unroll
;       for (int ni = 0; ni < 4; ++ni) bfr[s][ni] = *(const bf16x8*)(base + 16384 + (wn * 64 + ni * 16 + fr) * 128 + ch);
;     }
;     __builtin_amdgcn_s_setprio(1);
; #pragma unroll
;     for (int s = 0; s < 2; ++s)
; #pragma unroll
;       for (int mi = 0; mi < 4; ++mi)
; #pragma unroll
;         for (int ni = 0; ni < 4; ++ni) acc[mi][ni] = MFMA16(af[s][mi], bfr[s][ni], acc[mi][ni]);
;     __builtin_amdgcn_s_setprio(0);
;   };
;   const int nk = K >> 6;
;   if (!preloaded) { GLDS(0, 0) }
;   __syncthreads();
;   for (int kt = 0; kt < nk; ++kt) {
;     if (kt + 1 < nk) { GLDS((kt + 1) & 1, (kt + 1) << 6) }
;     compute(kt & 1);
;     __syncthreads();
	v_mov_b32_e32 v68, v66
	v_mov_b32_e32 v69, v66
	v_mov_b32_e32 v70, v66
	v_mov_b32_e32 v71, v66
	v_mov_b32_e32 v72, v66
	v_mov_b32_e32 v73, v66
	v_mov_b32_e32 v74, v66
	v_mov_b32_e32 v75, v66
	v_mov_b32_e32 v76, v66
	v_mov_b32_e32 v77, v66
	v_mov_b32_e32 v78, v66
	v_mov_b32_e32 v79, v66
	v_mov_b32_e32 v80, v66
	v_mov_b32_e32 v81, v66
	v_mov_b32_e32 v82, v66
	v_mov_b32_e32 v83, v66
	v_mov_b32_e32 v84, v66
	v_mov_b32_e32 v85, v66
	v_mov_b32_e32 v86, v66
	v_mov_b32_e32 v87, v66
	v_mov_b32_e32 v88, v66
	v_mov_b32_e32 v89, v66
	v_mov_b32_e32 v90, v66
	v_mov_b32_e32 v91, v66
	v_mov_b32_e32 v92, v66
	v_mov_b32_e32 v93, v66
	v_mov_b32_e32 v94, v66
	v_mov_b32_e32 v95, v66
	v_mov_b32_e32 v96, v66
	v_mov_b32_e32 v97, v66
	v_mov_b32_e32 v98, v66
	v_mov_b32_e32 v99, v66
	v_mov_b32_e32 v100, v66
	v_mov_b32_e32 v101, v66
	v_mov_b32_e32 v102, v66
	v_mov_b32_e32 v103, v66
	v_mov_b32_e32 v104, v66
	v_mov_b32_e32 v105, v66
	v_mov_b32_e32 v106, v66
	v_mov_b32_e32 v107, v66
	v_mov_b32_e32 v108, v66
	v_mov_b32_e32 v109, v66
	v_mov_b32_e32 v110, v66
	v_mov_b32_e32 v111, v66
	v_mov_b32_e32 v112, v66
	v_mov_b32_e32 v113, v66
	v_mov_b32_e32 v114, v66
	v_mov_b32_e32 v115, v66
	v_mov_b32_e32 v116, v66
	v_mov_b32_e32 v117, v66
	v_mov_b32_e32 v118, v66
	v_mov_b32_e32 v119, v66
	v_mov_b32_e32 v120, v66
	v_mov_b32_e32 v121, v66
	v_mov_b32_e32 v122, v66
	v_mov_b32_e32 v123, v66
	v_mov_b32_e32 v124, v66
	v_mov_b32_e32 v125, v66
	v_mov_b32_e32 v126, v66
	v_mov_b32_e32 v127, v66
	v_mov_b32_e32 v128, v66
	v_mov_b32_e32 v129, v66
	v_lshrrev_b32_e32 v246, 3, v158
	v_bfe_u32 v247, v158, 4, 3
	v_and_b32_e32 v0, 7, v158
	v_xor_b32_e32 v0, v0, v247
	v_lshlrev_b32_e32 v0, 4, v0
	v_mul_u32_u24_e32 v246, 0x880, v246
	v_add_u32_e32 v242, v246, v0
	v_add_u32_e32 v243, 0x11000, v242
	v_add_u32_e32 v244, 0x22000, v242
	v_add_u32_e32 v245, 0x33000, v242
	v_readfirstlane_b32 s50, v145
	s_waitcnt vmcnt(16) lgkmcnt(0)
	s_barrier
	.p2alignl 6, 3212836864
.LBB0_170:
	s_add_i32 s23, s22, 0x8000
	s_and_b32 s24, s23, 0x8000
	s_add_i32 m0, s50, s24
	s_and_b32 s22, s22, 0x8000
	global_load_lds_dwordx4 v242, s[40:41]
	s_addk_i32 m0, 0x1000
	s_nop 0
	global_load_lds_dwordx4 v243, s[40:41]
	s_addk_i32 m0, 0x1000
	s_nop 0
	global_load_lds_dwordx4 v244, s[40:41]
	s_addk_i32 m0, 0x1000
	s_nop 0
	global_load_lds_dwordx4 v245, s[40:41]
	s_addk_i32 m0, 0x1000
	s_nop 0
	global_load_lds_dwordx4 v242, s[42:43]
	s_addk_i32 m0, 0x1000
	s_nop 0
	global_load_lds_dwordx4 v243, s[42:43]
	s_addk_i32 m0, 0x1000
	s_nop 0
	global_load_lds_dwordx4 v244, s[42:43]
	s_addk_i32 m0, 0x1000
	s_nop 0
	global_load_lds_dwordx4 v245, s[42:43]
	s_add_u32 s40, s40, 0x80
	s_addc_u32 s41, s41, 0
	s_add_u32 s42, s42, 0x80
	s_addc_u32 s43, s43, 0
	v_or_b32_e32 v0, s22, v149
	v_add_u32_e32 v179, v0, v148
	v_add_u32_e32 v0, v0, v146
	ds_read_b128 v[150:153], v179
	ds_read_b128 v[154:157], v179 offset:2048
	ds_read_b128 v[180:183], v179 offset:4096
	ds_read_b128 v[184:187], v179 offset:6144
	ds_read_b128 v[188:191], v0 offset:16384
	ds_read_b128 v[192:195], v0 offset:18432
	ds_read_b128 v[196:199], v0 offset:20480
	ds_read_b128 v[200:203], v0 offset:22528
	v_or_b32_e32 v0, s22, v147
	v_add_u32_e32 v179, v0, v148
	v_add_u32_e32 v0, v0, v146
	ds_read_b128 v[204:207], v179
	ds_read_b128 v[208:211], v179 offset:2048
	ds_read_b128 v[212:215], v179 offset:4096
	ds_read_b128 v[216:219], v179 offset:6144
	ds_read_b128 v[220:223], v0 offset:16384
	ds_read_b128 v[224:227], v0 offset:18432
	ds_read_b128 v[228:231], v0 offset:20480
	ds_read_b128 v[232:235], v0 offset:22528
	s_setprio 1
	s_waitcnt lgkmcnt(8)
	v_mfma_f32_16x16x32_bf16 v[126:129], v[150:153], v[188:191], v[126:129]
	v_mfma_f32_16x16x32_bf16 v[122:125], v[150:153], v[192:195], v[122:125]
	v_mfma_f32_16x16x32_bf16 v[118:121], v[150:153], v[196:199], v[118:121]
	v_mfma_f32_16x16x32_bf16 v[114:117], v[150:153], v[200:203], v[114:117]
	v_mfma_f32_16x16x32_bf16 v[110:113], v[154:157], v[188:191], v[110:113]
	v_mfma_f32_16x16x32_bf16 v[106:109], v[154:157], v[192:195], v[106:109]
	v_mfma_f32_16x16x32_bf16 v[102:105], v[154:157], v[196:199], v[102:105]
	v_mfma_f32_16x16x32_bf16 v[98:101], v[154:157], v[200:203], v[98:101]
	v_mfma_f32_16x16x32_bf16 v[94:97], v[180:183], v[188:191], v[94:97]
	v_mfma_f32_16x16x32_bf16 v[90:93], v[180:183], v[192:195], v[90:93]
	v_mfma_f32_16x16x32_bf16 v[86:89], v[180:183], v[196:199], v[86:89]
	v_mfma_f32_16x16x32_bf16 v[82:85], v[180:183], v[200:203], v[82:85]
	v_mfma_f32_16x16x32_bf16 v[78:81], v[184:187], v[188:191], v[78:81]
	v_mfma_f32_16x16x32_bf16 v[74:77], v[184:187], v[192:195], v[74:77]
	v_mfma_f32_16x16x32_bf16 v[70:73], v[184:187], v[196:199], v[70:73]
	v_mfma_f32_16x16x32_bf16 v[66:69], v[184:187], v[200:203], v[66:69]
	s_waitcnt lgkmcnt(0)
	v_mfma_f32_16x16x32_bf16 v[126:129], v[204:207], v[220:223], v[126:129]
	v_mfma_f32_16x16x32_bf16 v[122:125], v[204:207], v[224:227], v[122:125]
	v_mfma_f32_16x16x32_bf16 v[118:121], v[204:207], v[228:231], v[118:121]
	v_mfma_f32_16x16x32_bf16 v[114:117], v[204:207], v[232:235], v[114:117]
	v_mfma_f32_16x16x32_bf16 v[110:113], v[208:211], v[220:223], v[110:113]
	v_mfma_f32_16x16x32_bf16 v[106:109], v[208:211], v[224:227], v[106:109]
	v_mfma_f32_16x16x32_bf16 v[102:105], v[208:211], v[228:231], v[102:105]
	v_mfma_f32_16x16x32_bf16 v[98:101], v[208:211], v[232:235], v[98:101]
	v_mfma_f32_16x16x32_bf16 v[94:97], v[212:215], v[220:223], v[94:97]
	v_mfma_f32_16x16x32_bf16 v[90:93], v[212:215], v[224:227], v[90:93]
	v_mfma_f32_16x16x32_bf16 v[86:89], v[212:215], v[228:231], v[86:89]
	v_mfma_f32_16x16x32_bf16 v[82:85], v[212:215], v[232:235], v[82:85]
	v_mfma_f32_16x16x32_bf16 v[78:81], v[216:219], v[220:223], v[78:81]
	v_mfma_f32_16x16x32_bf16 v[74:77], v[216:219], v[224:227], v[74:77]
	v_mfma_f32_16x16x32_bf16 v[70:73], v[216:219], v[228:231], v[70:73]
	v_mfma_f32_16x16x32_bf16 v[66:69], v[216:219], v[232:235], v[66:69]
	s_setprio 0
	s_add_u32 s8, s8, 0x80
	s_addc_u32 s9, s9, 0
	s_cmpk_eq_i32 s8, 0x780
	s_mov_b32 s22, s23
	s_waitcnt vmcnt(0)
	s_barrier
; #define MFMA16(a, b, c) __builtin_amdgcn_mfma_f32_16x16x32_bf16((a), (b), (c), 0, 0, 0)
; DI void gemm_tile(const bf16_t* __restrict__ A, int lda, const bf16_t* __restrict__ Bt, int ldb, int bvalid, int K, f32x4 (&acc)[4][4], char* lds, bool preloaded = false) {
;     ...
;   auto compute = [&](int st) {
;     const char* base = lds + st * 32768;
;     bf16x8 af[2][4], bfr[2][4];
; #pragma unroll
;     for (int s = 0; s < 2; ++s) {
;       const int ch = ((4 * s + fq) ^ fx) << 4;
; #pragma unroll
;       for (int mi = 0; mi < 4; ++mi) af[s][mi] = *(const bf16x8*)(base + (wm * 64 + mi * 16 + fr) * 128 + ch);
; #pragma unroll
;       for (int ni = 0; ni < 4; ++ni) bfr[s][ni] = *(const bf16x8*)(base + 16384 + (wn * 64 + ni * 16 + fr) * 128 + ch);
;     }
;     __builtin_amdgcn_s_setprio(1);
; #pragma unroll
;     for (int s = 0; s < 2; ++s)
; #pragma unroll
;       for (int mi = 0; mi < 4; ++mi)
; #pragma unroll
;         for (int ni = 0; ni < 4; ++ni) acc[mi][ni] = MFMA16(af[s][mi], bfr[s][ni], acc[mi][ni]);
;     __builtin_amdgcn_s_setprio(0);
; DI void phaseE_tile(const P& p, int layer, int mt, int nt, char* lds) {
;     ...
;   float* tile = (float*)lds;
;   stage_acc(acc, tile, wm, wn, fr, fq);
;   __syncthreads();
;   bf16_t* XB = (bf16_t*)(p.ws + W_XB);
;   float* SS = (float*)(p.ws + W_SS);
; #pragma unroll
;   for (int ps = 0; ps < 16; ++ps) {
;     const int lr = ps * 8 + wm * 4 + fq, row = row0 + lr;
;     const f32x4 v = xr[ps] + *(const f32x4*)(tile + lr * EPS + wn * 64 + fr * 4);
;     *(f32x4*)(XF + (size_t)row * DM + col) = v;
	s_cbranch_scc0 .LBB0_170
	v_add_u32_e32 v0, v149, v148
	ds_read_b128 v[132:135], v0 offset:32768
	ds_read_b128 v[136:139], v0 offset:34816
	ds_read_b128 v[150:153], v0 offset:36864
	ds_read_b128 v[154:157], v0 offset:38912
	v_add_u32_e32 v0, v149, v146
	ds_read_b128 v[180:183], v0 offset:49152
	ds_read_b128 v[184:187], v0 offset:51200
	ds_read_b128 v[188:191], v0 offset:53248
	ds_read_b128 v[192:195], v0 offset:55296
	v_add_u32_e32 v0, v147, v148
	ds_read_b128 v[196:199], v0 offset:32768
	ds_read_b128 v[200:203], v0 offset:34816
	ds_read_b128 v[204:207], v0 offset:36864
	ds_read_b128 v[208:211], v0 offset:38912
	v_add_u32_e32 v0, v147, v146
	ds_read_b128 v[146:149], v0 offset:49152
	ds_read_b128 v[212:215], v0 offset:51200
	ds_read_b128 v[216:219], v0 offset:53248
	ds_read_b128 v[220:223], v0 offset:55296
	s_setprio 1
	s_waitcnt lgkmcnt(9)
	v_mfma_f32_16x16x32_bf16 v[70:73], v[154:157], v[188:191], v[70:73]
	s_waitcnt lgkmcnt(8)
	v_mfma_f32_16x16x32_bf16 v[66:69], v[154:157], v[192:195], v[66:69]
	v_mfma_f32_16x16x32_bf16 v[126:129], v[132:135], v[180:183], v[126:129]
	v_mfma_f32_16x16x32_bf16 v[122:125], v[132:135], v[184:187], v[122:125]
	v_mfma_f32_16x16x32_bf16 v[118:121], v[132:135], v[188:191], v[118:121]
	v_mfma_f32_16x16x32_bf16 v[114:117], v[132:135], v[192:195], v[114:117]
	v_mfma_f32_16x16x32_bf16 v[110:113], v[136:139], v[180:183], v[110:113]
	v_mfma_f32_16x16x32_bf16 v[106:109], v[136:139], v[184:187], v[106:109]
	v_mfma_f32_16x16x32_bf16 v[102:105], v[136:139], v[188:191], v[102:105]
	v_mfma_f32_16x16x32_bf16 v[98:101], v[136:139], v[192:195], v[98:101]
	v_mfma_f32_16x16x32_bf16 v[94:97], v[150:153], v[180:183], v[94:97]
	v_mfma_f32_16x16x32_bf16 v[90:93], v[150:153], v[184:187], v[90:93]
	v_mfma_f32_16x16x32_bf16 v[86:89], v[150:153], v[188:191], v[86:89]
	v_mfma_f32_16x16x32_bf16 v[82:85], v[150:153], v[192:195], v[82:85]
	v_mfma_f32_16x16x32_bf16 v[78:81], v[154:157], v[180:183], v[78:81]
	v_mfma_f32_16x16x32_bf16 v[74:77], v[154:157], v[184:187], v[74:77]
	s_waitcnt lgkmcnt(1)
	v_mfma_f32_16x16x32_bf16 v[70:73], v[208:211], v[216:219], v[70:73]
	s_waitcnt lgkmcnt(0)
	v_mfma_f32_16x16x32_bf16 v[66:69], v[208:211], v[220:223], v[66:69]
	v_mfma_f32_16x16x32_bf16 v[126:129], v[196:199], v[146:149], v[126:129]
	v_mfma_f32_16x16x32_bf16 v[122:125], v[196:199], v[212:215], v[122:125]
	v_mfma_f32_16x16x32_bf16 v[118:121], v[196:199], v[216:219], v[118:121]
	v_mfma_f32_16x16x32_bf16 v[114:117], v[196:199], v[220:223], v[114:117]
	v_mfma_f32_16x16x32_bf16 v[110:113], v[200:203], v[146:149], v[110:113]
	v_mfma_f32_16x16x32_bf16 v[106:109], v[200:203], v[212:215], v[106:109]
	v_mfma_f32_16x16x32_bf16 v[102:105], v[200:203], v[216:219], v[102:105]
	v_mfma_f32_16x16x32_bf16 v[98:101], v[200:203], v[220:223], v[98:101]
	v_mfma_f32_16x16x32_bf16 v[94:97], v[204:207], v[146:149], v[94:97]
	v_mfma_f32_16x16x32_bf16 v[90:93], v[204:207], v[212:215], v[90:93]
	v_mfma_f32_16x16x32_bf16 v[86:89], v[204:207], v[216:219], v[86:89]
	v_mfma_f32_16x16x32_bf16 v[82:85], v[204:207], v[220:223], v[82:85]
	v_mfma_f32_16x16x32_bf16 v[78:81], v[208:211], v[146:149], v[78:81]
	v_mfma_f32_16x16x32_bf16 v[74:77], v[208:211], v[212:215], v[74:77]
	s_setprio 0
	v_lshlrev_b32_e32 v0, 2, v142
	v_lshl_or_b32 v132, s20, 6, v0
	v_lshl_or_b32 v0, s19, 8, v144
	v_mad_u64_u32 v[132:133], s[8:9], v132, s56, v[0:1]
	v_add_u32_e32 v0, 0x400, v132
	s_barrier
	ds_write2_b32 v132, v126, v122 offset1:16
	ds_write2_b32 v132, v127, v123 offset0:132 offset1:148
	ds_write2_b32 v0, v128, v124 offset0:8 offset1:24
	ds_write2_b32 v0, v129, v125 offset0:140 offset1:156
	ds_write2_b32 v132, v118, v114 offset0:32 offset1:48
	ds_write2_b32 v132, v119, v115 offset0:164 offset1:180
	ds_write2_b32 v0, v120, v116 offset0:40 offset1:56
	ds_write2_b32 v0, v121, v117 offset0:172 offset1:188
	v_add_u32_e32 v0, 0x2000, v132
	ds_write2_b32 v0, v110, v106 offset0:64 offset1:80
	ds_write2_b32 v0, v111, v107 offset0:196 offset1:212
	v_add_u32_e32 v106, 0x2400, v132
	ds_write2_b32 v106, v112, v108 offset0:72 offset1:88
	ds_write2_b32 v106, v113, v109 offset0:204 offset1:220
	ds_write2_b32 v0, v102, v98 offset0:96 offset1:112
	ds_write2_b32 v0, v103, v99 offset0:228 offset1:244
	ds_write2_b32 v106, v104, v100 offset0:104 offset1:120
	ds_write2_b32 v106, v105, v101 offset0:236 offset1:252
	v_add_u32_e32 v0, 0x4000, v132
	ds_write2_b32 v0, v94, v90 offset0:128 offset1:144
	v_add_u32_e32 v90, 0x4400, v132
	ds_write2_b32 v90, v95, v91 offset0:4 offset1:20
	ds_write2_b32 v90, v96, v92 offset0:136 offset1:152
	v_add_u32_e32 v91, 0x4800, v132
	ds_write2_b32 v91, v97, v93 offset0:12 offset1:28
	ds_write2_b32 v0, v86, v82 offset0:160 offset1:176
	ds_write2_b32 v90, v87, v83 offset0:36 offset1:52
	ds_write2_b32 v90, v88, v84 offset0:168 offset1:184
	ds_write2_b32 v91, v89, v85 offset0:44 offset1:60
	v_add_u32_e32 v0, 0x6000, v132
	ds_write2_b32 v0, v78, v74 offset0:192 offset1:208
	v_add_u32_e32 v74, 0x6400, v132
	ds_write2_b32 v74, v79, v75 offset0:68 offset1:84
	ds_write2_b32 v74, v80, v76 offset0:200 offset1:216
	v_add_u32_e32 v75, 0x6800, v132
	ds_write2_b32 v75, v81, v77 offset0:76 offset1:92
	ds_write2_b32 v0, v70, v66 offset0:224 offset1:240
	ds_write2_b32 v74, v71, v67 offset0:100 offset1:116
	ds_write2_b32 v74, v72, v68 offset0:232 offset1:248
	ds_write2_b32 v75, v73, v69 offset0:108 offset1:124
	v_or_b32_e32 v68, s11, v142
	v_lshlrev_b32_e32 v0, 2, v144
	v_lshl_add_u32 v0, s21, 2, v0
	v_mul_lo_u32 v66, v68, s56
	v_add_u32_e32 v0, v0, v66
	s_waitcnt lgkmcnt(0)
	s_barrier
	ds_read_b128 v[180:183], v0
	ds_read_b128 v[184:187], v0 offset:4224
	ds_read_b128 v[188:191], v0 offset:8448
	ds_read_b128 v[192:195], v0 offset:12672
	ds_read_b128 v[196:199], v0 offset:16896
	ds_read_b128 v[200:203], v0 offset:21120
	ds_read_b128 v[204:207], v0 offset:25344
	ds_read_b128 v[208:211], v0 offset:29568
	ds_read_b128 v[212:215], v0 offset:33792
	ds_read_b128 v[216:219], v0 offset:38016
	ds_read_b128 v[220:223], v0 offset:42240
	ds_read_b128 v[224:227], v0 offset:46464
	ds_read_b128 v[228:231], v0 offset:50688
	ds_read_b128 v[232:235], v0 offset:54912
	ds_read_b128 v[150:153], v0 offset:59136
	ds_read_b128 v[154:157], v0 offset:63360
	v_add_u32_e32 v70, s10, v68
	v_ashrrev_i32_e32 v71, 31, v70
	v_lshl_add_u64 v[66:67], v[130:131], 2, s[88:89]
	v_lshlrev_b64 v[68:69], 12, v[70:71]
	s_waitcnt lgkmcnt(15)
	v_pk_add_f32 v[4:5], v[4:5], v[182:183]
	v_pk_add_f32 v[2:3], v[2:3], v[180:181]
	v_lshl_add_u64 v[68:69], v[66:67], 0, v[68:69]
	s_and_b64 vcc, exec, s[38:39]
	s_mov_b64 s[8:9], -1
	global_store_dwordx4 v[68:69], v[2:5], off
	s_cbranch_vccnz .LBB0_173
	s_mov_b64 s[8:9], 0
